# ssm pass 3 scan: B_bar*u by eight 4x4x4 16-block bf16 MFMAs per four steps instead of 64 v_dot2c
# speedup vs baseline: 1.0249x; 1.0112x over previous
; __device__ __forceinline__ unsigned cvt_pk_bf16(float lo, float hi) { unsigned r; asm volatile("v_cvt_pk_bf16_f32 %0, %1, %2" : "=v"(r) : "v"(lo), "v"(hi)); return r; }
; #define LAS __attribute__((address_space(3)))
; __device__ __forceinline__ void ssm_pass3h(CArgs* ap, const float* COEF, int l, const bf16_t* PROJ, const float* SST, bf16_t* YS, LAS unsigned char* wlds, int unit, int lane) {
;     ...
;     unsigned bbr2[8], bbi2[8];
; #pragma unroll
;     for (int k = 0; k < 8; ++k) { bbr2[k] = cvt_pk_bf16(bbr[2 * k], bbr[2 * k + 1]); bbi2[k] = cvt_pk_bf16(bbi[2 * k], bbi[2 * k + 1]); }
;     float cmB[32];
; #pragma unroll
;     for (int j = 0; j < 8; ++j) {
;         const int k0 = 16 * j + 4 * fq;
;         const float* src = (j < 4 ? ap->in[16] : ap->in[17]) + ((size_t)(l * 32 + g) * 16 + fr) * 64 + (j < 4 ? k0 : k0 - 64);
;         const f32x4 c4 = *(const f32x4*)src;
; #pragma unroll
;         for (int r = 0; r < 4; ++r) cmB[4 * j + r] = (j < 4) ? c4[r] : -c4[r];
;     }
;     const float dsk = ap->in[18][l * 512 + g * 16 + fr];
;     float tr = abr, ti = abi;
; #pragma unroll
;     for (int k = 0; k < 7; ++k) { const float nr = tr * tr - ti * ti, ni = 2.f * tr * ti; tr = nr; ti = ni; }
;     float hr = 0.f, hi = 0.f;
;     const float* sp = SST + ((size_t)(unit - c) * 64 + lane) * 2;
;     int cc = 0;
;     for (; cc + 8 <= c; cc += 8) {
;         float2 s8[8];
; #pragma unroll
;         for (int j = 0; j < 8; ++j) s8[j] = *(const float2*)(sp + (size_t)(cc + j) * 128);
; #pragma unroll
;         for (int j = 0; j < 8; ++j) { const float nr = tr * hr - ti * hi + s8[j].x, ni = tr * hi + ti * hr + s8[j].y; hr = nr; hi = ni; }
;     }
;     for (; cc < c; ++cc) { const float2 s = *(const float2*)(sp + (size_t)cc * 128); const float nr = tr * hr - ti * hi + s.x, ni = tr * hi + ti * hr + s.y; hr = nr; hi = ni; }
;     const size_t row0 = (size_t)(b * SEQ + c * 128);
;     const bf16_t* up = PROJ + row0 * INW + 2560 + g * 16;
;     LAS float* Hf = (LAS float*)wlds;
;     u32x4 wn[8];
; #pragma unroll
;     for (int tt = 0; tt < 4; ++tt) { wn[2 * tt] = ((const u32x4*)(up + (size_t)tt * INW))[0]; wn[2 * tt + 1] = ((const u32x4*)(up + (size_t)tt * INW))[1]; }
.LBB0_148:
	v_mov_b32_e32 v208, v101
	v_mov_b32_e32 v209, v103
	v_mov_b32_e32 v210, v102
	v_mov_b32_e32 v211, v104
	v_mov_b32_e32 v212, v105
	v_mov_b32_e32 v213, v107
	v_mov_b32_e32 v214, v106
	v_mov_b32_e32 v215, v108
	v_mov_b32_e32 v216, v109
	v_mov_b32_e32 v217, v111
	v_mov_b32_e32 v218, v110
	v_mov_b32_e32 v219, v112
	v_mov_b32_e32 v220, v113
	v_mov_b32_e32 v221, v115
	v_mov_b32_e32 v222, v114
	v_mov_b32_e32 v223, v116
	s_lshl_b32 s0, s9, 2
	s_and_b32 s0, s0, 0xffffe000
	s_lshl_b32 s1, s3, 7
	s_or_b32 s0, s0, s1
	s_ashr_i32 s1, s0, 31
	s_mul_i32 s10, s0, 0x4800
	s_mul_hi_i32 s3, s0, 0x4800
	s_add_u32 s10, s68, s10
	s_addc_u32 s3, s69, s3
	s_lshl_b32 s78, s2, 1
	s_add_u32 s10, s10, s78
	s_addc_u32 s11, s3, 0
	s_add_u32 s2, s10, 0x1400
	s_addc_u32 s3, s11, 0
	s_add_u32 s12, s10, 0x5c00
	v_mov_b32_e32 v0, 0x5000
	global_load_dwordx4 v[20:23], v1, s[2:3] offset:16
	global_load_dwordx4 v[24:27], v198, s[10:11] offset:1024
	s_addc_u32 s13, s11, 0
	global_load_dwordx4 v[32:35], v0, s[10:11] offset:3072
	v_mov_b32_e32 v0, 0xa000
	global_load_dwordx4 v[28:31], v1, s[12:13] offset:16
	global_load_dwordx4 v[40:43], v0, s[10:11] offset:1024
	s_add_u32 s12, s10, 0xa400
	s_addc_u32 s13, s11, 0
	v_mov_b32_e32 v0, 0xe000
	global_load_dwordx4 v[36:39], v1, s[12:13] offset:16
	global_load_dwordx4 v[48:51], v0, s[10:11] offset:3072
	s_add_u32 s12, s10, 0xec00
	s_addc_u32 s13, s11, 0
	global_load_dwordx4 v[44:47], v1, s[12:13] offset:16
	v_lshl_add_u64 v[92:93], v[80:81], 0, s[78:79]
	v_pk_mov_b32 v[94:95], v[2:3], v[2:3] op_sel:[1,0]
	s_mov_b32 s10, 0
	s_waitcnt vmcnt(12)
	v_xor_b32_e32 v89, 0x80000000, v64
	v_xor_b32_e32 v117, 0x80000000, v65
	v_xor_b32_e32 v118, 0x80000000, v66
	v_xor_b32_e32 v119, 0x80000000, v67
	s_waitcnt vmcnt(11)
	v_xor_b32_e32 v120, 0x80000000, v60
	v_xor_b32_e32 v121, 0x80000000, v61
	v_xor_b32_e32 v122, 0x80000000, v62
	v_xor_b32_e32 v123, 0x80000000, v63
	s_waitcnt vmcnt(10)
	v_xor_b32_e32 v124, 0x80000000, v56
	v_xor_b32_e32 v125, 0x80000000, v57
	v_xor_b32_e32 v126, 0x80000000, v58
	v_xor_b32_e32 v127, 0x80000000, v59
	s_waitcnt vmcnt(9)
	v_xor_b32_e32 v128, 0x80000000, v52
	v_xor_b32_e32 v129, 0x80000000, v53
	v_xor_b32_e32 v130, 0x80000000, v54
	v_xor_b32_e32 v131, 0x80000000, v55
	s_mov_b32 s11, 0

; __device__ __forceinline__ void ssm_pass3h(CArgs* ap, const float* COEF, int l, const bf16_t* PROJ, const float* SST, bf16_t* YS, LAS unsigned char* wlds, int unit, int lane) {
;     ...
;             u32x4 wc[8];
; #pragma unroll
;             for (int j = 0; j < 8; ++j) wc[j] = wn[j];
;             const int tn = (t + 4 < 128) ? t + 4 : t;
; #pragma unroll
;             for (int tt = 0; tt < 4; ++tt) { wn[2 * tt] = ((const u32x4*)(up + (size_t)(tn + tt) * INW))[0]; wn[2 * tt + 1] = ((const u32x4*)(up + (size_t)(tn + tt) * INW))[1]; }
; #pragma unroll
;             for (int tt = 0; tt < 4; ++tt) {
;                 const u32x4 w0 = wc[2 * tt], w1 = wc[2 * tt + 1];
;                 const unsigned u2[8] = {w0.x, w0.y, w0.z, w0.w, w1.x, w1.y, w1.z, w1.w};
;                 float br_ = 0.f, bi_ = 0.f;
; #pragma unroll
;                 for (int k = 0; k < 8; ++k) { br_ = __builtin_amdgcn_fdot2_f32_bf16(__builtin_bit_cast(bf16x2v, bbr2[k]), __builtin_bit_cast(bf16x2v, u2[k]), br_, false);
;                                                bi_ = __builtin_amdgcn_fdot2_f32_bf16(__builtin_bit_cast(bf16x2v, bbi2[k]), __builtin_bit_cast(bf16x2v, u2[k]), bi_, false); }
;                 const float nr = abr * hr - abi * hi + br_, ni = abr * hi + abi * hr + bi_; hr = nr; hi = ni;
;                 Hf[(4 * q + tt) * 132 + lane] = hr; Hf[(4 * q + tt) * 132 + 64 + lane] = hi;
;             }
.LBB0_150:
	s_add_i32 s13, s14, 4
	s_cmpk_lt_u32 s14, 0x7c
	s_cselect_b32 s14, s13, s14
	s_mul_i32 s78, s14, 0x2400
	s_lshl_b64 s[14:15], s[78:79], 1
	s_add_u32 s14, s2, s14
	s_waitcnt vmcnt(7)
	v_mov_b64_e32 v[138:139], v[22:23]
	s_waitcnt vmcnt(6)
	v_mov_b64_e32 v[142:143], v[26:27]
	s_addc_u32 s15, s3, s15
	v_mov_b64_e32 v[136:137], v[20:21]
	v_mov_b64_e32 v[140:141], v[24:25]
	global_load_dwordx4 v[20:23], v1, s[14:15] offset:16
	global_load_dwordx4 v[24:27], v1, s[14:15]
	s_add_i32 s14, s78, 0x2400
	s_mov_b32 s15, s79
	s_lshl_b64 s[14:15], s[14:15], 1
	s_add_u32 s14, s2, s14
	s_waitcnt vmcnt(7)
	v_mov_b64_e32 v[70:71], v[30:31]
	s_waitcnt vmcnt(6)
	v_mov_b64_e32 v[74:75], v[34:35]
	s_addc_u32 s15, s3, s15
	v_mov_b64_e32 v[68:69], v[28:29]
	v_mov_b64_e32 v[72:73], v[32:33]
	global_load_dwordx4 v[28:31], v1, s[14:15] offset:16
	global_load_dwordx4 v[32:35], v1, s[14:15]
	s_add_i32 s14, s78, 0x4800
	s_mov_b32 s15, s79
	s_lshl_b64 s[14:15], s[14:15], 1
	s_add_u32 s14, s2, s14
	s_waitcnt vmcnt(7)
	v_mov_b64_e32 v[62:63], v[38:39]
	s_waitcnt vmcnt(6)
	v_mov_b64_e32 v[66:67], v[42:43]
	s_addc_u32 s15, s3, s15
	s_addk_i32 s78, 0x6c00
	v_mov_b64_e32 v[60:61], v[36:37]
	v_mov_b64_e32 v[64:65], v[40:41]
	global_load_dwordx4 v[36:39], v1, s[14:15] offset:16
	global_load_dwordx4 v[40:43], v1, s[14:15]
	s_lshl_b64 s[14:15], s[78:79], 1
	s_add_u32 s14, s2, s14
	s_waitcnt vmcnt(7)
	v_mov_b64_e32 v[54:55], v[46:47]
	s_waitcnt vmcnt(6)
	v_mov_b64_e32 v[58:59], v[50:51]
	s_addc_u32 s15, s3, s15
	v_mov_b64_e32 v[52:53], v[44:45]
	v_mov_b64_e32 v[56:57], v[48:49]
	global_load_dwordx4 v[44:47], v1, s[14:15] offset:16
	global_load_dwordx4 v[48:51], v1, s[14:15]
	v_and_b32_e32 v0, 3, v166
	v_cmp_eq_u32_e32 vcc, 1, v0
	v_add_u32_e32 v97, s12, v99
	v_add_u32_e32 v184, 32, v97
	v_cndmask_b32_e32 v176, v140, v72, vcc
	v_cndmask_b32_e32 v177, v141, v73, vcc
	v_cndmask_b32_e32 v178, v142, v74, vcc
	v_cndmask_b32_e32 v179, v143, v75, vcc
	v_cndmask_b32_e32 v180, v136, v68, vcc
	v_cndmask_b32_e32 v181, v137, v69, vcc
	v_cndmask_b32_e32 v182, v138, v70, vcc
	v_cndmask_b32_e32 v183, v139, v71, vcc
	v_cmp_eq_u32_e32 vcc, 2, v0
	v_add_u32_e32 v185, 48, v97
	s_nop 0
	v_cndmask_b32_e32 v176, v176, v64, vcc
	v_cndmask_b32_e32 v177, v177, v65, vcc
	v_cndmask_b32_e32 v178, v178, v66, vcc
	v_cndmask_b32_e32 v179, v179, v67, vcc
	v_cndmask_b32_e32 v180, v180, v60, vcc
	v_cndmask_b32_e32 v181, v181, v61, vcc
	v_cndmask_b32_e32 v182, v182, v62, vcc
	v_cndmask_b32_e32 v183, v183, v63, vcc
	v_cmp_eq_u32_e32 vcc, 3, v0
	s_nop 1
	v_cndmask_b32_e32 v176, v176, v56, vcc
	v_cndmask_b32_e32 v177, v177, v57, vcc
	v_cndmask_b32_e32 v178, v178, v58, vcc
	v_cndmask_b32_e32 v179, v179, v59, vcc
	v_cndmask_b32_e32 v180, v180, v52, vcc
	v_cndmask_b32_e32 v181, v181, v53, vcc
	v_cndmask_b32_e32 v182, v182, v54, vcc
	v_cndmask_b32_e32 v183, v183, v55, vcc
	v_mfma_f32_4x4x4_16b_bf16 v[144:147], v[176:177], v[208:209], 0
	v_mfma_f32_4x4x4_16b_bf16 v[148:151], v[176:177], v[210:211], 0
	s_nop 0
	v_mfma_f32_4x4x4_16b_bf16 v[144:147], v[178:179], v[212:213], v[144:147]
	v_mfma_f32_4x4x4_16b_bf16 v[148:151], v[178:179], v[214:215], v[148:151]
	s_nop 0
	v_mfma_f32_4x4x4_16b_bf16 v[144:147], v[180:181], v[216:217], v[144:147]
	v_mfma_f32_4x4x4_16b_bf16 v[148:151], v[180:181], v[218:219], v[148:151]
	s_nop 0
	v_mfma_f32_4x4x4_16b_bf16 v[144:147], v[182:183], v[220:221], v[144:147]
	v_mfma_f32_4x4x4_16b_bf16 v[148:151], v[182:183], v[222:223], v[148:151]
	s_nop 0
	s_nop 1
	v_pk_mul_f32 v[152:153], v[2:3], v[90:91]
	v_pk_mul_f32 v[154:155], v[94:95], v[90:91]
	v_sub_f32_e32 v152, v152, v153
	v_add_f32_e32 v153, v154, v155
	v_add_f32_e32 v90, v144, v152
	v_add_f32_e32 v91, v148, v153
	ds_write2st64_b32 v97, v90, v91 offset1:1
	v_pk_mul_f32 v[152:153], v[2:3], v[90:91]
	v_pk_mul_f32 v[154:155], v[94:95], v[90:91]
	v_sub_f32_e32 v152, v152, v153
	v_add_f32_e32 v153, v154, v155
	v_add_f32_e32 v90, v145, v152
	v_add_f32_e32 v91, v149, v153
	ds_write2_b32 v97, v90, v91 offset0:132 offset1:196
	v_pk_mul_f32 v[152:153], v[2:3], v[90:91]
	v_pk_mul_f32 v[154:155], v[94:95], v[90:91]
	v_sub_f32_e32 v152, v152, v153
	v_add_f32_e32 v153, v154, v155
	v_add_f32_e32 v90, v146, v152
	v_add_f32_e32 v91, v150, v153
	ds_write2st64_b32 v184, v90, v91 offset0:4 offset1:5
	v_pk_mul_f32 v[152:153], v[2:3], v[90:91]
	v_pk_mul_f32 v[154:155], v[94:95], v[90:91]
	v_sub_f32_e32 v152, v152, v153
	v_add_f32_e32 v153, v154, v155
	v_add_f32_e32 v90, v147, v152
	v_add_f32_e32 v91, v151, v153
	ds_write2st64_b32 v185, v90, v91 offset0:6 offset1:7
	s_addk_i32 s12, 0x840
	s_cmpk_eq_i32 s12, 0x2100
	s_mov_b32 s14, s13
	s_cbranch_scc0 .LBB0_150
; __device__ __forceinline__ float gelu_t(float x) { const float p = __builtin_fmaf(x * x, -0.10294324f, -2.30220819f); return x * __builtin_amdgcn_rcpf(1.f + __builtin_amdgcn_exp2f(x * p)); }
; #define LAS __attribute__((address_space(3)))
; __device__ __forceinline__ unsigned f2bf(float f) { unsigned u = __builtin_bit_cast(unsigned, f); return (u + 0x7fffu + ((u >> 16) & 1u)) >> 16; }
; __device__ __forceinline__ void ssm_pass3h(CArgs* ap, const float* COEF, int l, const bf16_t* PROJ, const float* SST, bf16_t* YS, LAS unsigned char* wlds, int unit, int lane) {
;     ...
;         asm volatile("s_waitcnt lgkmcnt(0)" ::: "memory");
;         f32x4 y = (f32x4){0.f, 0.f, 0.f, 0.f};
; #pragma unroll
;         for (int j = 0; j < 8; ++j) {
;             const f32x4 a4 = *(const LAS f32x4*)(Hf + fr * 132 + 16 * j + 4 * fq);
; #pragma unroll
;             for (int r = 0; r < 4; ++r) y = __builtin_amdgcn_mfma_f32_16x16x4f32(a4[r], cmB[4 * j + r], y, 0, 0, 0);
;         }
;         asm volatile("s_waitcnt lgkmcnt(0)" ::: "memory");
; #pragma unroll
;         for (int i = 0; i < 4; ++i) {
;             const size_t row = row0 + 16 * blk + 4 * fq + i;
;             YS[row * 512 + g * 16 + fr] = (bf16_t)f2bf(gelu_t(y[i] + dsk * __uint_as_float(((unsigned)uq[i]) << 16)));
;         }
	s_waitcnt lgkmcnt(0)
	ds_read_b128 v[144:147], v100
	ds_read_b128 v[148:151], v100 offset:64
	ds_read_b128 v[152:155], v100 offset:128
	ds_read_b128 v[168:171], v100 offset:192
	ds_read_b128 v[172:175], v100 offset:256
	ds_read_b128 v[176:179], v100 offset:320
	ds_read_b128 v[180:183], v100 offset:384
	ds_read_b128 v[184:187], v100 offset:448
	s_waitcnt vmcnt(11)
	v_lshlrev_b32_e32 v57, 16, v135
	v_mov_b32_e32 v97, v1
	v_or_b32_e32 v0, 1, v96
	v_or_b32_e32 v58, 2, v96
	v_mov_b32_e32 v59, v1
	v_or_b32_e32 v56, 3, v96
	s_add_i32 s11, s11, 1
	s_add_i32 s10, s10, 16
	s_cmp_eq_u32 s11, 8
	v_lshl_add_u64 v[60:61], v[96:97], 0, s[0:1]
	v_lshlrev_b64 v[60:61], 10, v[60:61]
	v_lshl_add_u64 v[60:61], v[92:93], 0, v[60:61]
	s_waitcnt lgkmcnt(6)
	v_mfma_f32_16x16x4_f32 v[52:55], v144, v4, 0
	v_mfma_f32_16x16x4_f32 v[188:191], v148, v8, 0
	v_mfma_f32_16x16x4_f32 v[52:55], v145, v5, v[52:55]
	v_mfma_f32_16x16x4_f32 v[188:191], v149, v9, v[188:191]
	v_mfma_f32_16x16x4_f32 v[52:55], v146, v6, v[52:55]
	v_mfma_f32_16x16x4_f32 v[188:191], v150, v10, v[188:191]
	v_mfma_f32_16x16x4_f32 v[52:55], v147, v7, v[52:55]
	v_mfma_f32_16x16x4_f32 v[188:191], v151, v11, v[188:191]
	s_waitcnt lgkmcnt(4)
	v_mfma_f32_16x16x4_f32 v[52:55], v152, v12, v[52:55]
	v_mfma_f32_16x16x4_f32 v[188:191], v168, v16, v[188:191]
	v_mfma_f32_16x16x4_f32 v[52:55], v153, v13, v[52:55]
	v_mfma_f32_16x16x4_f32 v[188:191], v169, v17, v[188:191]
	v_mfma_f32_16x16x4_f32 v[52:55], v154, v14, v[52:55]
	v_mfma_f32_16x16x4_f32 v[188:191], v170, v18, v[188:191]
	v_mfma_f32_16x16x4_f32 v[52:55], v155, v15, v[52:55]
	v_mfma_f32_16x16x4_f32 v[188:191], v171, v19, v[188:191]
	s_waitcnt lgkmcnt(2)
	v_mfma_f32_16x16x4_f32 v[52:55], v172, v89, v[52:55]
	v_mfma_f32_16x16x4_f32 v[188:191], v176, v120, v[188:191]
	v_mfma_f32_16x16x4_f32 v[52:55], v173, v117, v[52:55]
	v_mfma_f32_16x16x4_f32 v[188:191], v177, v121, v[188:191]
	v_mfma_f32_16x16x4_f32 v[52:55], v174, v118, v[52:55]
	v_mfma_f32_16x16x4_f32 v[188:191], v178, v122, v[188:191]
	v_mfma_f32_16x16x4_f32 v[52:55], v175, v119, v[52:55]
	v_mfma_f32_16x16x4_f32 v[188:191], v179, v123, v[188:191]
	s_waitcnt lgkmcnt(0)
	v_mfma_f32_16x16x4_f32 v[52:55], v180, v124, v[52:55]
	v_mfma_f32_16x16x4_f32 v[188:191], v184, v128, v[188:191]
	v_mfma_f32_16x16x4_f32 v[52:55], v181, v125, v[52:55]
	v_mfma_f32_16x16x4_f32 v[188:191], v185, v129, v[188:191]
	v_mfma_f32_16x16x4_f32 v[52:55], v182, v126, v[52:55]
	v_mfma_f32_16x16x4_f32 v[188:191], v186, v130, v[188:191]
	v_mfma_f32_16x16x4_f32 v[52:55], v183, v127, v[52:55]
	v_mfma_f32_16x16x4_f32 v[188:191], v187, v131, v[188:191]
	s_nop 9
	s_nop 1
	v_add_f32_e32 v52, v52, v188
	v_add_f32_e32 v53, v53, v189
	v_add_f32_e32 v54, v54, v190
	v_add_f32_e32 v55, v55, v191
	v_fma_f32 v52, v87, v57, v52
	v_mul_f32_e32 v57, v52, v52
	v_fmamk_f32 v57, v57, 0xbdd2d3e8, v196
	v_mul_f32_e32 v57, v52, v57
	v_exp_f32_e32 v57, v57
	s_nop 0
	v_add_f32_e32 v57, 1.0, v57
	v_rcp_f32_e32 v57, v57
	s_nop 0
	v_mul_f32_e32 v52, v52, v57
	v_bfe_u32 v57, v52, 16, 1
	v_add3_u32 v52, v52, v57, s80
	global_store_short_d16_hi v[60:61], v52, off
	v_lshl_add_u64 v[60:61], v[0:1], 0, s[0:1]
	s_waitcnt vmcnt(11)
	v_lshlrev_b32_e32 v0, 16, v134
	v_fma_f32 v0, v87, v0, v53
	v_mul_f32_e32 v52, v0, v0
	v_fmamk_f32 v52, v52, 0xbdd2d3e8, v196
	v_mul_f32_e32 v52, v0, v52
	v_exp_f32_e32 v52, v52
	v_mov_b32_e32 v57, v1
	v_add_f32_e32 v52, 1.0, v52
	v_rcp_f32_e32 v52, v52
	s_nop 0
	v_mul_f32_e32 v0, v0, v52
	v_bfe_u32 v52, v0, 16, 1
	v_add3_u32 v0, v0, v52, s80
	v_lshlrev_b64 v[52:53], 10, v[60:61]
	v_lshl_add_u64 v[52:53], v[92:93], 0, v[52:53]
	global_store_short_d16_hi v[52:53], v0, off
	s_waitcnt vmcnt(11)
	v_lshlrev_b32_e32 v0, 16, v133
	v_fma_f32 v0, v87, v0, v54
	v_mul_f32_e32 v54, v0, v0
	v_fmamk_f32 v54, v54, 0xbdd2d3e8, v196
	v_mul_f32_e32 v54, v0, v54
	v_exp_f32_e32 v54, v54
	v_lshl_add_u64 v[52:53], v[58:59], 0, s[0:1]
	v_lshlrev_b64 v[52:53], 10, v[52:53]
	v_lshl_add_u64 v[52:53], v[92:93], 0, v[52:53]
	v_add_f32_e32 v54, 1.0, v54
	v_rcp_f32_e32 v54, v54
	s_nop 0
	v_mul_f32_e32 v0, v0, v54
	v_bfe_u32 v54, v0, 16, 1
	v_add3_u32 v0, v0, v54, s80
	global_store_short_d16_hi v[52:53], v0, off
	s_waitcnt vmcnt(11)
	v_lshlrev_b32_e32 v0, 16, v132
	v_fmac_f32_e32 v55, v87, v0
	v_mul_f32_e32 v0, v55, v55
	v_fmamk_f32 v0, v0, 0xbdd2d3e8, v196
	v_mul_f32_e32 v0, v55, v0
	v_exp_f32_e32 v0, v0
	v_lshl_add_u64 v[52:53], v[56:57], 0, s[0:1]
	v_lshlrev_b64 v[52:53], 10, v[52:53]
	v_lshl_add_u64 v[52:53], v[92:93], 0, v[52:53]
	v_add_f32_e32 v0, 1.0, v0
	v_rcp_f32_e32 v0, v0
	s_nop 0
	v_mul_f32_e32 v0, v55, v0
	v_bfe_u32 v54, v0, 16, 1
	v_add3_u32 v0, v0, v54, s80
	global_store_short_d16_hi v[52:53], v0, off
	s_cbranch_scc0 .LBB0_149
	s_add_i32 s9, s9, s33
	s_cmpk_gt_i32 s9, 0xfff
	s_cbranch_scc0 .LBB0_141
